# hot loop heads (3 GEMM K-loops, 3 attention tile loops, norm loop) aligned to 64 B (on top of v36)
# baseline (speedup 1.0000x reference)
; template <class Epi, class Sched, bool ALIGN_EPI = false, bool SP2 = false>
; __device__ __forceinline__ void gemm_phase(PG8_LAS unsigned char* lds, const Gemm g, const Sched& S, const Epi& E, const int tid_in) {
;     ...
; #pragma unroll
;         for (int a = 0; a < 2; ++a)
; #pragma unroll
;             for (int b = 0; b < 2; ++b)
; #pragma unroll
;                 for (int m = 0; m < 4; ++m)
; #pragma unroll
;                     for (int n = 0; n < 2; ++n) acc[a][b][m][n] = (f32x4){0.f, 0.f, 0.f, 0.f};
;         cur = nxt; cA = nA; cB = nB; ++ui;
.LBB0_41:
	s_add_i32 s57, s57, 1
	s_mul_i32 s2, s57, s73
	s_mul_hi_u32 s3, s57, s88
	s_add_i32 s3, s3, s2
	s_mul_i32 s2, s57, s88
	s_add_u32 s2, s2, s74
	s_addc_u32 s3, s3, s75
	v_mov_b64_e32 v[0:1], s[96:97]
	v_cmp_lt_i64_e64 s[8:9], s[2:3], v[0:1]
	s_and_b64 s[10:11], s[8:9], exec
	s_cselect_b32 s2, s2, 0
	s_ashr_i32 s3, s2, 31
	s_lshr_b32 s3, s3, 29
	s_add_i32 s3, s2, s3
	s_ashr_i32 s10, s3, 3
	s_and_b32 s3, s3, -8
	s_sub_i32 s2, s2, s3
	s_cmp_lt_i32 s2, 0
	s_cselect_b32 s3, s43, s42
	s_mul_i32 s2, s3, s2
	s_add_i32 s12, s2, s10
	s_abs_i32 s3, s12
	s_mul_hi_u32 s10, s3, s47
	s_mul_i32 s11, s10, s45
	s_ashr_i32 s2, s12, 31
	s_sub_i32 s3, s3, s11
	s_xor_b32 s2, s2, s46
	s_add_i32 s11, s10, 1
	s_sub_i32 s13, s3, s45
	s_cmp_ge_u32 s3, s45
	s_cselect_b32 s10, s11, s10
	s_cselect_b32 s3, s13, s3
	s_add_i32 s11, s10, 1
	s_cmp_ge_u32 s3, s45
	s_cselect_b32 s3, s11, s10
	s_xor_b32 s3, s3, s2
	s_sub_i32 s13, s3, s2
	s_lshl_b32 s14, s13, 3
	s_sub_i32 s2, 0x88, s14
	s_min_i32 s15, s2, 8
	s_abs_i32 s23, s15
	v_cvt_f32_u32_e32 v0, s23
	s_mov_b32 s2, s24
	s_sub_i32 s24, 0, s23
	s_mul_i32 s13, s13, s44
	v_rcp_iflag_f32_e32 v0, v0
	s_sub_i32 s12, s12, s13
	s_mov_b32 s3, s22
	s_abs_i32 s22, s12
	v_mul_f32_e32 v0, 0x4f7ffffe, v0
	v_cvt_u32_f32_e32 v0, v0
	s_xor_b32 s13, s12, s15
	s_mov_b64 s[10:11], s[26:27]
	s_ashr_i32 s13, s13, 31
	v_readfirstlane_b32 s25, v0
	s_mul_i32 s24, s24, s25
	s_mul_hi_u32 s24, s25, s24
	s_add_i32 s25, s25, s24
	s_mul_hi_u32 s24, s22, s25
	s_mul_i32 s25, s24, s23
	s_sub_i32 s22, s22, s25
	s_add_i32 s25, s24, 1
	s_sub_i32 s26, s22, s23
	s_cmp_ge_u32 s22, s23
	s_cselect_b32 s24, s25, s24
	s_cselect_b32 s22, s26, s22
	s_add_i32 s25, s24, 1
	s_cmp_ge_u32 s22, s23
	s_cselect_b32 s22, s25, s24
	s_xor_b32 s22, s22, s13
	s_sub_i32 s22, s22, s13
	s_mul_i32 s13, s22, s15
	s_sub_i32 s12, s12, s13
	s_add_i32 s24, s12, s14
	s_ashr_i32 s25, s24, 31
	s_lshl_b64 s[12:13], s[24:25], 19
	s_mov_b64 s[4:5], s[30:31]
	s_add_u32 s30, s82, s12
	s_addc_u32 s31, s83, s13
	s_and_b64 s[12:13], s[8:9], exec
	s_cselect_b32 s14, s31, s5
	s_cselect_b32 s15, s30, s4
	s_ashr_i32 s23, s22, 31
	s_lshl_b64 s[12:13], s[22:23], 19
	s_add_u32 s26, s39, s12
	s_addc_u32 s27, s40, s13
	s_and_b64 s[12:13], s[8:9], exec
	s_cselect_b32 s23, s27, s11
	s_cselect_b32 s25, s26, s10
	s_add_u32 s4, s4, 0x40080
	s_addc_u32 s5, s5, 0
	s_add_u32 s58, s10, 0x100
	v_mov_b32_e32 v0, 0
	s_addc_u32 s59, s11, 0
	s_mov_b32 s60, -2
	v_mov_b32_e32 v1, v0
	v_mov_b32_e32 v2, v0
	v_mov_b32_e32 v3, v0
	v_mov_b32_e32 v4, v0
	v_mov_b32_e32 v5, v0
	v_mov_b32_e32 v6, v0
	v_mov_b32_e32 v7, v0
	v_mov_b32_e32 v16, v0
	v_mov_b32_e32 v17, v0
	v_mov_b32_e32 v18, v0
	v_mov_b32_e32 v19, v0
	v_mov_b32_e32 v20, v0
	v_mov_b32_e32 v21, v0
	v_mov_b32_e32 v22, v0
	v_mov_b32_e32 v23, v0
	v_mov_b32_e32 v32, v0
	v_mov_b32_e32 v33, v0
	v_mov_b32_e32 v34, v0
	v_mov_b32_e32 v35, v0
	v_mov_b32_e32 v36, v0
	v_mov_b32_e32 v37, v0
	v_mov_b32_e32 v38, v0
	v_mov_b32_e32 v39, v0
	v_mov_b32_e32 v48, v0
	v_mov_b32_e32 v49, v0
	v_mov_b32_e32 v50, v0
	v_mov_b32_e32 v51, v0
	v_mov_b32_e32 v52, v0
	v_mov_b32_e32 v53, v0
	v_mov_b32_e32 v54, v0
	v_mov_b32_e32 v55, v0
	v_mov_b32_e32 v8, v0
	v_mov_b32_e32 v9, v0
	v_mov_b32_e32 v10, v0
	v_mov_b32_e32 v11, v0
	v_mov_b32_e32 v12, v0
	v_mov_b32_e32 v13, v0
	v_mov_b32_e32 v14, v0
	v_mov_b32_e32 v15, v0
	v_mov_b32_e32 v24, v0
	v_mov_b32_e32 v25, v0
	v_mov_b32_e32 v26, v0
	v_mov_b32_e32 v27, v0
	v_mov_b32_e32 v28, v0
	v_mov_b32_e32 v29, v0
	v_mov_b32_e32 v30, v0
	v_mov_b32_e32 v31, v0
	v_mov_b32_e32 v40, v0
	v_mov_b32_e32 v41, v0
	v_mov_b32_e32 v42, v0
	v_mov_b32_e32 v43, v0
	v_mov_b32_e32 v44, v0
	v_mov_b32_e32 v45, v0
	v_mov_b32_e32 v46, v0
	v_mov_b32_e32 v47, v0
	v_mov_b32_e32 v60, v0
	v_mov_b32_e32 v61, v0
	v_mov_b32_e32 v62, v0
	v_mov_b32_e32 v63, v0
	v_mov_b32_e32 v72, v0
	v_mov_b32_e32 v73, v0
	v_mov_b32_e32 v74, v0
	v_mov_b32_e32 v75, v0
	v_mov_b32_e32 v80, v0
	v_mov_b32_e32 v81, v0
	v_mov_b32_e32 v82, v0
	v_mov_b32_e32 v83, v0
	v_mov_b32_e32 v84, v0
	v_mov_b32_e32 v85, v0
	v_mov_b32_e32 v86, v0
	v_mov_b32_e32 v87, v0
	v_mov_b32_e32 v96, v0
	v_mov_b32_e32 v97, v0
	v_mov_b32_e32 v98, v0
	v_mov_b32_e32 v99, v0
	v_mov_b32_e32 v100, v0
	v_mov_b32_e32 v101, v0
	v_mov_b32_e32 v102, v0
	v_mov_b32_e32 v103, v0
	v_mov_b32_e32 v112, v0
	v_mov_b32_e32 v113, v0
	v_mov_b32_e32 v114, v0
	v_mov_b32_e32 v115, v0
	v_mov_b32_e32 v116, v0
	v_mov_b32_e32 v117, v0
	v_mov_b32_e32 v118, v0
	v_mov_b32_e32 v119, v0
	v_mov_b32_e32 v128, v0
	v_mov_b32_e32 v129, v0
	v_mov_b32_e32 v130, v0
	v_mov_b32_e32 v131, v0
	v_mov_b32_e32 v132, v0
	v_mov_b32_e32 v133, v0
	v_mov_b32_e32 v134, v0
	v_mov_b32_e32 v135, v0
	v_mov_b32_e32 v88, v0
	v_mov_b32_e32 v89, v0
	v_mov_b32_e32 v90, v0
	v_mov_b32_e32 v91, v0
	v_mov_b32_e32 v92, v0
	v_mov_b32_e32 v93, v0
	v_mov_b32_e32 v94, v0
	v_mov_b32_e32 v95, v0
	v_mov_b32_e32 v104, v0
	v_mov_b32_e32 v105, v0
	v_mov_b32_e32 v106, v0
	v_mov_b32_e32 v107, v0
	v_mov_b32_e32 v108, v0
	v_mov_b32_e32 v109, v0
	v_mov_b32_e32 v110, v0
	v_mov_b32_e32 v111, v0
	v_mov_b32_e32 v120, v0
	v_mov_b32_e32 v121, v0
	v_mov_b32_e32 v122, v0
	v_mov_b32_e32 v123, v0
	v_mov_b32_e32 v124, v0
	v_mov_b32_e32 v125, v0
	v_mov_b32_e32 v126, v0
	v_mov_b32_e32 v127, v0
	v_mov_b32_e32 v136, v0
	v_mov_b32_e32 v137, v0
	v_mov_b32_e32 v138, v0
	v_mov_b32_e32 v139, v0
	v_mov_b32_e32 v140, v0
	v_mov_b32_e32 v141, v0
	v_mov_b32_e32 v142, v0
	v_mov_b32_e32 v143, v0
	.p2align	6

; template <int KIND> ...
;     ...
; #pragma unroll
;                 for (int j = 0; j < 16; ++j) s0[j] = __builtin_amdgcn_exp2f(s0[j]);
;                 bf16x8 pf[4];
; #pragma unroll
;                 for (int s = 0; s < 2; ++s) { u32x4 w; w.x = pk2n(s0[8 * s + 0], s0[8 * s + 1]); w.y = pk2n(s0[8 * s + 2], s0[8 * s + 3]); w.z = pk2n(s0[8 * s + 4], s0[8 * s + 5]); w.w = pk2n(s0[8 * s + 6], s0[8 * s + 7]);
;                     pf[s] = __builtin_bit_cast(bf16x8, w); }
;                 __builtin_amdgcn_sched_barrier(0);
; #pragma unroll
;                 for (int s = 0; s < 2; ++s)
; #pragma unroll
;                     for (int dt = 0; dt < NDT; ++dt) {
;                         vfb[s][dt][0] = __builtin_amdgcn_ds_read_tr16_b64_v4i16((LAS s16x4*)(lds + buf * VBUF + voff + (16 * (s + 2)) * VSTR + 64 * dt));
;                         vfb[s][dt][1] = __builtin_amdgcn_ds_read_tr16_b64_v4i16((LAS s16x4*)(lds + buf * VBUF + voff + (16 * (s + 2) + 8) * VSTR + 64 * dt)); }
;                 {
;                     constexpr int NM = 2 * (1 + NDT);
;                     int mi = 0;
; #pragma unroll
;                     for (int s = 0; s < 2; ++s) {
;                         lacc = __builtin_amdgcn_mfma_f32_32x32x16_bf16(ones, pf[s], lacc, 0, 0, 0);
; #pragma unroll
;                         for (int j = (mi * 16) / NM; j < ((mi + 1) * 16) / NM; ++j) s1[j] = __builtin_amdgcn_exp2f(s1[j]);
;                         ++mi;
; #pragma unroll
;                         for (int dt = 0; dt < NDT; ++dt) {
;                             const s16x4 va = vfa[s][dt][0], vb = vfa[s][dt][1];
;                             const bf16x8 vf = {va[0], va[1], va[2], va[3], vb[0], vb[1], vb[2], vb[3]};
;                             o[dt] = __builtin_amdgcn_mfma_f32_32x32x16_bf16(vf, pf[s], o[dt], 0, 0, 0);
; #pragma unroll
;                             for (int j = (mi * 16) / NM; j < ((mi + 1) * 16) / NM; ++j) s1[j] = __builtin_amdgcn_exp2f(s1[j]);
;                             ++mi;
;                         }
;                     }
; #pragma unroll
;                     for (int q = 0; q < 2; ++q) { u32x4 w; w.x = pk2n(s1[8 * q + 0], s1[8 * q + 1]); w.y = pk2n(s1[8 * q + 2], s1[8 * q + 3]); w.z = pk2n(s1[8 * q + 4], s1[8 * q + 5]); w.w = pk2n(s1[8 * q + 6], s1[8 * q + 7]);
;                         pf[q + 2] = __builtin_bit_cast(bf16x8, w); }
; #pragma unroll
.LBB0_109:
	s_nop 0
	v_exp_f32_e32 v80, v80
	v_exp_f32_e32 v81, v81
	v_exp_f32_e32 v82, v82
	v_exp_f32_e32 v83, v83
	v_exp_f32_e32 v84, v84
	v_exp_f32_e32 v85, v85
	v_exp_f32_e32 v86, v86
	v_exp_f32_e32 v87, v87
	v_exp_f32_e32 v88, v88
	v_exp_f32_e32 v89, v89
	v_exp_f32_e32 v90, v90
	v_exp_f32_e32 v91, v91
	v_exp_f32_e32 v92, v92
	v_exp_f32_e32 v93, v93
	v_exp_f32_e32 v94, v94
	v_exp_f32_e32 v95, v95
	v_cvt_pk_bf16_f32 v80, v80, v81
	v_cvt_pk_bf16_f32 v81, v82, v83
	v_cvt_pk_bf16_f32 v82, v84, v85
	v_cvt_pk_bf16_f32 v83, v86, v87
	v_cvt_pk_bf16_f32 v84, v88, v89
	v_cvt_pk_bf16_f32 v85, v90, v91
	v_cvt_pk_bf16_f32 v86, v92, v93
	v_cvt_pk_bf16_f32 v87, v94, v95
	s_waitcnt lgkmcnt(6)
	v_mfma_f32_32x32x16_bf16 v[16:31], v[132:135], v[80:83], v[16:31]
	v_mov_b64_e32 v[90:91], s[86:87]
	v_mov_b64_e32 v[88:89], s[84:85]
	v_exp_f32_e32 v92, v64
	v_exp_f32_e32 v93, v65
	ds_read_b64_tr_b16 v[64:65], v161 offset:24576
	v_mfma_f32_32x32x16_bf16 v[48:63], v[88:91], v[80:83], v[48:63]
	v_exp_f32_e32 v94, v66
	v_exp_f32_e32 v95, v67
	v_exp_f32_e32 v132, v68
	v_exp_f32_e32 v133, v69
	ds_read_b64_tr_b16 v[66:67], v161 offset:26112
	ds_read_b64_tr_b16 v[68:69], v161 offset:24640
	s_waitcnt lgkmcnt(7)
	v_mfma_f32_32x32x16_bf16 v[0:15], v[128:131], v[80:83], v[0:15]
	v_exp_f32_e32 v134, v70
	v_exp_f32_e32 v135, v71
	v_exp_f32_e32 v128, v72
	v_exp_f32_e32 v129, v73
	ds_read_b64_tr_b16 v[70:71], v161 offset:26176
	ds_read_b64_tr_b16 v[72:73], v161 offset:27648
	v_mfma_f32_32x32x16_bf16 v[48:63], v[88:91], v[84:87], v[48:63]
	v_exp_f32_e32 v130, v74
	v_exp_f32_e32 v131, v75
	v_exp_f32_e32 v162, v76
	v_exp_f32_e32 v163, v77
	ds_read_b64_tr_b16 v[74:75], v161 offset:29184
	ds_read_b64_tr_b16 v[76:77], v161 offset:27712
	s_waitcnt lgkmcnt(9)
	v_mfma_f32_32x32x16_bf16 v[16:31], v[124:127], v[84:87], v[16:31]
	v_exp_f32_e32 v164, v78
	v_exp_f32_e32 v165, v79
	v_cvt_pk_bf16_f32 v80, v92, v93
	v_cvt_pk_bf16_f32 v81, v94, v95
	ds_read_b64_tr_b16 v[78:79], v161 offset:29248
	s_waitcnt lgkmcnt(8)
	v_mfma_f32_32x32x16_bf16 v[0:15], v[120:123], v[84:87], v[0:15]
	v_cvt_pk_bf16_f32 v82, v132, v133
	v_cvt_pk_bf16_f32 v83, v134, v135
	v_cvt_pk_bf16_f32 v84, v128, v129
	v_cvt_pk_bf16_f32 v85, v130, v131
	v_cvt_pk_bf16_f32 v86, v162, v163
	v_cvt_pk_bf16_f32 v87, v164, v165
	s_waitcnt lgkmcnt(6)
	v_mfma_f32_32x32x16_bf16 v[16:31], v[64:67], v[80:83], v[16:31]
	s_and_b32 s17, s11, 1
	s_mul_i32 s19, s17, 0x2400
	s_mulk_i32 s17, 0x3000
	v_add_u32_e32 v182, s19, v153
	s_waitcnt vmcnt(1)
	ds_write_b128 v182, v[96:99]
	v_add_u32_e32 v182, s17, v154
	s_waitcnt vmcnt(0)
	ds_write_b128 v182, v[100:103] offset:18432
	s_waitcnt lgkmcnt(6)
	v_mfma_f32_32x32x16_bf16 v[0:15], v[68:71], v[80:83], v[0:15]
	v_mfma_f32_32x32x16_bf16 v[48:63], v[88:91], v[80:83], v[48:63]
	s_waitcnt lgkmcnt(4)
	v_mfma_f32_32x32x16_bf16 v[16:31], v[72:75], v[84:87], v[16:31]
	s_waitcnt lgkmcnt(2)
	v_mfma_f32_32x32x16_bf16 v[0:15], v[76:79], v[84:87], v[0:15]
	v_mfma_f32_32x32x16_bf16 v[48:63], v[88:91], v[84:87], v[48:63]
	s_add_i32 s10, s10, 1
	v_add_u32_e32 v160, 64, v160
	s_cmp_eq_u32 s5, s10
	v_add_u32_e32 v145, 64, v145
	s_waitcnt lgkmcnt(0)
	s_barrier
	s_cbranch_scc1 .LBB0_112
	.p2align	6

; #define LAS __attribute__((address_space(3)))
; template <int KIND> ...
;     ...
;         int base1 = b * 4096, n1 = 64, kr_lo = 0, rs_w = 0, qr = 0, qc = 0, cs = 0;
;         if (KIND == 0) { const int r0 = qb * 4; kr_lo = min(max(r0 - 4, 0), 56); const int kr_hi = min(max(r0 - 1, 0), 56) + 8; base1 += kr_lo * 64; n1 = kr_hi - kr_lo;
;             qr = r0 + (wid >> 1); rs_w = min(max(qr - 4, 0), 56); qc = 32 * (wid & 1) + l32; cs = min(max(qc - 8, 0), 48); }
;         if (isctx) n1 = 0;
;         const int base2 = M_LAT + b * 256, nt = n1 + 4;
;         bf16x8 qf[4];
;         { const bf16_t* qp = qkv + (size_t)(qrow0 + qoff + l32) * N + hq * 64 + 8 * hi;
; #pragma unroll
;           for (int t = 0; t < 4; ++t) qf[t] = *(const bf16x8*)(qp + 16 * t); }
;         if (KIND == 0 && !isctx) { LAS float* bt = (LAS float*)(lds + OFF_BIAS); for (int i = tid; i < 465; i += NTHREADS) bt[i] = rpb[h * 465 + i] * LOG2E; }
;         u32x4 kreg[NK], vreg[NVC];
;         const int krow_l = tid >> 3, kpart = tid & 7;
;     ...
;         float m_ref = 0.f; int first = 1;
;         f32x16 o[NDT], lacc, mneg;
; #pragma unroll
;         for (int dt = 0; dt < NDT; ++dt)
; #pragma unroll
;             for (int j = 0; j < 16; ++j) o[dt][j] = 0.f;
; #pragma unroll
;         for (int j = 0; j < 16; ++j) { lacc[j] = 0.f; mneg[j] = 0.f; }
;         const bf16x8 ones = {(short)0x3F80, (short)0x3F80, (short)0x3F80, (short)0x3F80, (short)0x3F80, (short)0x3F80, (short)0x3F80, (short)0x3F80};
;         ATT_LOAD(0); ATT_STORE(0); __syncthreads();
;         const int koff = kidx * KT + l32 * KSTR + 16 * hi;
;         const int voff = OFF_V + (4 * hi + ((lane & 15) >> 2)) * VSTR + (16 * ((lane >> 4) & 1) + 4 * (lane & 3)) * 2;
;         const int wb = 4 * hi - cs;
;         const int boff0 = OFF_BIAS + 4 * (cs - qc + 15 + wb);
.LBB0_143:
	s_or_b64 exec, exec, s[82:83]
	s_lshl_b32 s75, s81, 2
	v_sub_u32_e64 v0, s75, 1 clamp
	s_max_u32 s90, s75, 4
	v_readfirstlane_b32 s10, v0
	s_min_u32 s10, s10, 56
	s_lshl_b32 s8, s74, 6
	s_lshl_b32 s2, s2, 8
	s_sub_i32 s10, s10, s90
	s_add_i32 s9, s8, 0x800
	s_add_i32 s2, s2, 0x8000
	s_add_i32 s10, s10, 12
	s_and_b64 s[76:77], exec, s[78:79]
	s_cselect_b32 s80, 0, s10
	s_lshl_b32 s10, s80, 6
	v_sub_u32_e64 v4, s75, 4 clamp
	s_sub_i32 s10, s2, s10
	v_lshlrev_b32_e32 v0, 6, v4
	s_cmp_gt_i32 s80, 0
	v_add_u32_e32 v0, s5, v0
	v_mov_b32_e32 v1, s10
	s_cselect_b64 vcc, -1, 0
	v_readlane_b32 s10, v255, 5
	v_cndmask_b32_e32 v5, v1, v0, vcc
	v_readlane_b32 s11, v255, 6
	v_add_u32_e32 v2, v5, v208
	v_add_u32_e32 v5, v5, v209
	v_mov_b64_e32 v[0:1], s[10:11]
	s_movk_i32 s10, 0x1800
	v_mad_i64_i32 v[2:3], s[76:77], v2, s10, v[0:1]
	s_lshl_b32 s96, s8, 1
	v_mad_i64_i32 v[0:1], s[76:77], v5, s10, v[0:1]
	v_lshl_add_u64 v[2:3], v[2:3], 0, s[96:97]
	s_lshl_b32 s76, s9, 1
	s_mov_b32 s77, s97
	v_lshl_add_u64 v[2:3], v[2:3], 0, v[192:193]
	v_lshl_add_u64 v[0:1], v[0:1], 0, s[76:77]
	v_lshl_add_u64 v[0:1], v[154:155], 1, v[0:1]
	global_load_dwordx4 v[128:131], v[2:3], off offset:2048
	global_load_dwordx4 v[132:135], v[0:1], off
	v_readfirstlane_b32 s74, v4
	s_cmp_lt_i32 s80, -3
	s_mov_b32 s83, 0
	s_waitcnt vmcnt(1)
	ds_write_b128 v210, v[128:131]
	s_waitcnt vmcnt(0)
	ds_write_b128 v211, v[132:135] offset:18432
	s_waitcnt lgkmcnt(0)
	s_barrier
	s_cbranch_scc1 .LBB0_166
	v_readlane_b32 s8, v255, 41
	s_add_i32 s75, s75, s8
	s_max_i32 s8, s75, 4
	s_add_i32 s8, s8, -4
	s_min_u32 s75, s8, 56
	s_mulk_i32 s90, 0x7c
	s_mul_i32 s8, s81, 0x1f0
	v_mov_b32_e32 v46, v193
	v_mov_b32_e32 v47, v193
	s_sub_i32 s8, s90, s8
	v_mov_b32_e32 v32, v193
	v_mov_b32_e32 v33, v193
	v_mov_b32_e32 v34, v193
	v_mov_b32_e32 v35, v193
	v_mov_b32_e32 v36, v193
	v_mov_b32_e32 v37, v193
	v_mov_b32_e32 v38, v193
	v_mov_b32_e32 v39, v193
	v_mov_b32_e32 v40, v193
	v_mov_b32_e32 v41, v193
	v_mov_b32_e32 v42, v193
	v_mov_b32_e32 v43, v193
	v_mov_b32_e32 v44, v193
	v_mov_b32_e32 v45, v193
	v_mov_b32_e32 v16, 0
	v_mov_b64_e32 v[62:63], v[46:47]
	s_add_i32 s95, s80, 4
	s_mov_b32 s82, 1
	v_lshl_add_u64 v[202:203], v[156:157], 0, s[96:97]
	v_lshl_add_u64 v[204:205], v[158:159], 0, s[76:77]
	s_add_i32 s76, s75, 8
	s_sub_i32 s77, 0, s80
	v_add_u32_e32 v237, s8, v235
	v_mov_b64_e32 v[60:61], v[44:45]
	v_mov_b64_e32 v[58:59], v[42:43]
	v_mov_b64_e32 v[56:57], v[40:41]
	v_mov_b64_e32 v[54:55], v[38:39]
	v_mov_b64_e32 v[52:53], v[36:37]
	v_mov_b64_e32 v[50:51], v[34:35]
	v_mov_b64_e32 v[48:49], v[32:33]
	v_mov_b32_e32 v17, v16
	v_mov_b32_e32 v18, v16
	v_mov_b32_e32 v19, v16
	v_mov_b32_e32 v20, v16
	v_mov_b32_e32 v21, v16
	v_mov_b32_e32 v22, v16
	v_mov_b32_e32 v23, v16
	v_mov_b32_e32 v24, v16
	v_mov_b32_e32 v25, v16
	v_mov_b32_e32 v26, v16
	v_mov_b32_e32 v27, v16
	v_mov_b32_e32 v28, v16
	v_mov_b32_e32 v29, v16
	v_mov_b32_e32 v30, v16
	v_mov_b32_e32 v31, v16
	v_mov_b32_e32 v0, v16
	v_mov_b32_e32 v1, v16
	v_mov_b32_e32 v2, v16
	v_mov_b32_e32 v3, v16
	v_mov_b32_e32 v4, v16
	v_mov_b32_e32 v5, v16
	v_mov_b32_e32 v6, v16
	v_mov_b32_e32 v7, v16
	v_mov_b32_e32 v8, v16
	v_mov_b32_e32 v9, v16
	v_mov_b32_e32 v10, v16
	v_mov_b32_e32 v11, v16
	v_mov_b32_e32 v12, v16
	v_mov_b32_e32 v13, v16
	v_mov_b32_e32 v14, v16
	v_mov_b32_e32 v15, v16
	.p2align	6

; template <int KIND> ...
;     ...
;         for (int t = 0; t < nt; ++t) {
;     ...
;             if (t + 1 < nt) ATT_STORE((t + 1) & 1);
;             __syncthreads();
;         }
.LBB0_188:
	s_add_i32 s16, s16, 1
	v_add_u32_e32 v250, 64, v250
	v_add_u32_e32 v249, 64, v249
	s_cmp_eq_u32 s3, s16
	v_add_u32_e32 v248, 64, v248
	s_waitcnt vmcnt(0) lgkmcnt(0)
	s_barrier
	s_cbranch_scc1 .LBB0_195
	.p2align	6

; template <bool SRCB> ...
;     ...
;     for (int g = gw; g < M_LAT / 4; g += NGW) norm_rows<4, SRCB>(4 * g, g >> 10, SRCB ? (const void*)((const bf16_t*)hsrc_lat + (size_t)g * 4 * DM) : (const void*)((const float*)hsrc_lat + (size_t)g * 4 * DM), hout, final_out, Y, nullptr, w, gpost, gate, U, gpre, shift, scale, lane);
.LBB0_210:
	v_readlane_b32 s2, v254, 52
	s_add_i32 s23, s23, s76
	s_add_i32 s8, s8, s82
	v_readlane_b32 s3, v254, 53
	s_cmpk_gt_i32 s23, 0x1fff
	s_nop 0
	v_lshl_add_u64 v[112:113], v[112:113], 0, s[2:3]
	s_cbranch_scc1 .LBB0_245
	.p2align	6

; template <class Epi, class Sched, bool ALIGN_EPI = false, bool SP2 = false>
; __device__ __forceinline__ void gemm_phase(PG8_LAS unsigned char* lds, const Gemm g, const Sched& S, const Epi& E, const int tid_in) {
;     ...
;         const bool has_next = S.next(ui + 1, nxt);
;         const char* nA = has_next ? (const char*)g.A + (size_t)nxt.pm * tstep + (size_t)nxt.k0 * 2 : cA; const char* nB = has_next ? (const char*)g.Bt + (size_t)nxt.pn * tstep + (size_t)nxt.k0 * 2 : cB;
;         const int nt = cur.nt;
;         for (int t = 0; t < nt; t += 2) {
;     ...
; #pragma unroll
;         for (int a = 0; a < 2; ++a)
; #pragma unroll
;             for (int b = 0; b < 2; ++b)
; #pragma unroll
;                 for (int m = 0; m < 4; ++m)
; #pragma unroll
;                     for (int n = 0; n < 2; ++n) acc[a][b][m][n] = (f32x4){0.f, 0.f, 0.f, 0.f};
;         cur = nxt; cA = nA; cB = nB; ++ui;
.LBB0_282:
	s_cmp_eq_u32 s50, 0
	s_cbranch_scc1 .LBB0_294
	s_add_i32 s28, s50, -2
	s_add_u32 s24, s24, 0x80
	s_addc_u32 s25, s25, 0
	s_add_u32 s29, s26, 0x100
	v_mov_b32_e32 v0, 0
	s_addc_u32 s51, s27, 0
	s_mov_b32 s26, 0
	v_mov_b32_e32 v1, v0
	v_mov_b32_e32 v2, v0
	v_mov_b32_e32 v3, v0
	v_mov_b32_e32 v4, v0
	v_mov_b32_e32 v5, v0
	v_mov_b32_e32 v6, v0
	v_mov_b32_e32 v7, v0
	v_mov_b32_e32 v16, v0
	v_mov_b32_e32 v17, v0
	v_mov_b32_e32 v18, v0
	v_mov_b32_e32 v19, v0
	v_mov_b32_e32 v20, v0
	v_mov_b32_e32 v21, v0
	v_mov_b32_e32 v22, v0
	v_mov_b32_e32 v23, v0
	v_mov_b32_e32 v32, v0
	v_mov_b32_e32 v33, v0
	v_mov_b32_e32 v34, v0
	v_mov_b32_e32 v35, v0
	v_mov_b32_e32 v36, v0
	v_mov_b32_e32 v37, v0
	v_mov_b32_e32 v38, v0
	v_mov_b32_e32 v39, v0
	v_mov_b32_e32 v48, v0
	v_mov_b32_e32 v49, v0
	v_mov_b32_e32 v50, v0
	v_mov_b32_e32 v51, v0
	v_mov_b32_e32 v52, v0
	v_mov_b32_e32 v53, v0
	v_mov_b32_e32 v54, v0
	v_mov_b32_e32 v55, v0
	v_mov_b32_e32 v8, v0
	v_mov_b32_e32 v9, v0
	v_mov_b32_e32 v10, v0
	v_mov_b32_e32 v11, v0
	v_mov_b32_e32 v12, v0
	v_mov_b32_e32 v13, v0
	v_mov_b32_e32 v14, v0
	v_mov_b32_e32 v15, v0
	v_mov_b32_e32 v24, v0
	v_mov_b32_e32 v25, v0
	v_mov_b32_e32 v26, v0
	v_mov_b32_e32 v27, v0
	v_mov_b32_e32 v28, v0
	v_mov_b32_e32 v29, v0
	v_mov_b32_e32 v30, v0
	v_mov_b32_e32 v31, v0
	v_mov_b32_e32 v40, v0
	v_mov_b32_e32 v41, v0
	v_mov_b32_e32 v42, v0
	v_mov_b32_e32 v43, v0
	v_mov_b32_e32 v44, v0
	v_mov_b32_e32 v45, v0
	v_mov_b32_e32 v46, v0
	v_mov_b32_e32 v47, v0
	v_mov_b32_e32 v56, v0
	v_mov_b32_e32 v57, v0
	v_mov_b32_e32 v58, v0
	v_mov_b32_e32 v59, v0
	v_mov_b32_e32 v60, v0
	v_mov_b32_e32 v61, v0
	v_mov_b32_e32 v62, v0
	v_mov_b32_e32 v63, v0
	v_mov_b32_e32 v64, v0
	v_mov_b32_e32 v65, v0
	v_mov_b32_e32 v66, v0
	v_mov_b32_e32 v67, v0
	v_mov_b32_e32 v68, v0
	v_mov_b32_e32 v69, v0
	v_mov_b32_e32 v70, v0
	v_mov_b32_e32 v71, v0
	v_mov_b32_e32 v80, v0
	v_mov_b32_e32 v81, v0
	v_mov_b32_e32 v82, v0
	v_mov_b32_e32 v83, v0
	v_mov_b32_e32 v84, v0
	v_mov_b32_e32 v85, v0
	v_mov_b32_e32 v86, v0
	v_mov_b32_e32 v87, v0
	v_mov_b32_e32 v96, v0
	v_mov_b32_e32 v97, v0
	v_mov_b32_e32 v98, v0
	v_mov_b32_e32 v99, v0
	v_mov_b32_e32 v100, v0
	v_mov_b32_e32 v101, v0
	v_mov_b32_e32 v102, v0
	v_mov_b32_e32 v103, v0
	v_mov_b32_e32 v112, v0
	v_mov_b32_e32 v113, v0
	v_mov_b32_e32 v114, v0
	v_mov_b32_e32 v115, v0
	v_mov_b32_e32 v116, v0
	v_mov_b32_e32 v117, v0
	v_mov_b32_e32 v118, v0
	v_mov_b32_e32 v119, v0
	v_mov_b32_e32 v72, v0
	v_mov_b32_e32 v73, v0
	v_mov_b32_e32 v74, v0
	v_mov_b32_e32 v75, v0
	v_mov_b32_e32 v76, v0
	v_mov_b32_e32 v77, v0
	v_mov_b32_e32 v78, v0
	v_mov_b32_e32 v79, v0
	v_mov_b32_e32 v88, v0
	v_mov_b32_e32 v89, v0
	v_mov_b32_e32 v90, v0
	v_mov_b32_e32 v91, v0
	v_mov_b32_e32 v92, v0
	v_mov_b32_e32 v93, v0
	v_mov_b32_e32 v94, v0
	v_mov_b32_e32 v95, v0
	v_mov_b32_e32 v104, v0
	v_mov_b32_e32 v105, v0
	v_mov_b32_e32 v106, v0
	v_mov_b32_e32 v107, v0
	v_mov_b32_e32 v108, v0
	v_mov_b32_e32 v109, v0
	v_mov_b32_e32 v110, v0
	v_mov_b32_e32 v111, v0
	v_mov_b32_e32 v120, v0
	v_mov_b32_e32 v121, v0
	v_mov_b32_e32 v122, v0
	v_mov_b32_e32 v123, v0
	v_mov_b32_e32 v124, v0
	v_mov_b32_e32 v125, v0
	v_mov_b32_e32 v126, v0
	v_mov_b32_e32 v127, v0
	.p2align	6

; template <class Epi, class Sched, bool ALIGN_EPI = false, bool SP2 = false>
; __device__ __forceinline__ void gemm_phase(PG8_LAS unsigned char* lds, const Gemm g, const Sched& S, const Epi& E, const int tid_in) {
;     ...
; #pragma unroll
;         for (int a = 0; a < 2; ++a)
; #pragma unroll
;             for (int b = 0; b < 2; ++b)
; #pragma unroll
;                 for (int m = 0; m < 4; ++m)
; #pragma unroll
;                     for (int n = 0; n < 2; ++n) acc[a][b][m][n] = (f32x4){0.f, 0.f, 0.f, 0.f};
;         cur = nxt; cA = nA; cB = nB; ++ui;
.LBB0_306:
	s_add_i32 s38, s38, 1
	s_mul_i32 s2, s38, s73
	s_mul_hi_u32 s3, s38, s88
	s_add_i32 s3, s3, s2
	s_mul_i32 s2, s38, s88
	s_add_u32 s2, s2, s74
	s_addc_u32 s3, s3, s75
	v_mov_b64_e32 v[0:1], s[96:97]
	v_cmp_lt_i64_e64 s[6:7], s[2:3], v[0:1]
	s_mov_b64 s[4:5], s[16:17]
	s_and_b64 s[16:17], s[6:7], exec
	s_cselect_b32 s2, s2, 0
	s_ashr_i32 s3, s2, 31
	s_lshr_b32 s3, s3, 29
	s_add_i32 s3, s2, s3
	s_ashr_i32 s9, s3, 3
	s_and_b32 s3, s3, -8
	s_sub_i32 s2, s2, s3
	s_cmp_lt_i32 s2, 0
	s_cselect_b32 s3, s29, s28
	s_mul_i32 s2, s3, s2
	s_add_i32 s9, s2, s9
	s_mul_hi_i32 s2, s9, 0x2e8ba2e9
	s_lshr_b32 s3, s2, 31
	s_ashr_i32 s2, s2, 5
	s_add_i32 s11, s2, s3
	s_lshl_b32 s16, s11, 3
	s_sub_i32 s2, s24, s16
	s_min_i32 s17, s2, 8
	s_abs_i32 s22, s17
	v_cvt_f32_u32_e32 v0, s22
	s_mulk_i32 s11, 0xb0
	s_mov_b64 s[20:21], s[12:13]
	s_sub_i32 s9, s9, s11
	v_rcp_iflag_f32_e32 v0, v0
	s_sub_i32 s11, 0, s22
	s_mov_b32 s3, s10
	s_abs_i32 s10, s9
	v_mul_f32_e32 v0, 0x4f7ffffe, v0
	v_cvt_u32_f32_e32 v0, v0
	s_mov_b32 s2, s8
	s_xor_b32 s8, s9, s17
	s_ashr_i32 s8, s8, 31
	v_readfirstlane_b32 s12, v0
	s_mul_i32 s11, s11, s12
	s_mul_hi_u32 s11, s12, s11
	s_add_i32 s12, s12, s11
	s_mul_hi_u32 s11, s10, s12
	s_mul_i32 s12, s11, s22
	s_sub_i32 s10, s10, s12
	s_add_i32 s12, s11, 1
	s_sub_i32 s13, s10, s22
	s_cmp_ge_u32 s10, s22
	s_cselect_b32 s11, s12, s11
	s_cselect_b32 s10, s13, s10
	s_add_i32 s12, s11, 1
	s_cmp_ge_u32 s10, s22
	s_cselect_b32 s10, s12, s11
	s_xor_b32 s10, s10, s8
	s_sub_i32 s8, s10, s8
	s_mul_i32 s10, s8, s17
	s_sub_i32 s9, s9, s10
	s_add_i32 s10, s16, s9
	s_ashr_i32 s11, s10, 31
	s_lshl_b64 s[12:13], s[10:11], 19
	s_add_u32 s16, s50, s12
	s_addc_u32 s17, s51, s13
	s_and_b64 s[12:13], s[6:7], exec
	s_cselect_b32 s11, s17, s5
	s_cselect_b32 s39, s16, s4
	s_ashr_i32 s9, s8, 31
	s_lshl_b64 s[12:13], s[8:9], 19
	s_add_u32 s12, s25, s12
	s_addc_u32 s13, s26, s13
	s_and_b64 s[22:23], s[6:7], exec
	s_cselect_b32 s9, s13, s21
	s_cselect_b32 s40, s12, s20
	s_add_u32 s4, s4, 0x40080
	s_addc_u32 s5, s5, 0
	s_add_u32 s41, s20, 0x100
	v_mov_b32_e32 v0, 0
	s_addc_u32 s42, s21, 0
	s_mov_b32 s43, -2
	v_mov_b32_e32 v1, v0
	v_mov_b32_e32 v2, v0
	v_mov_b32_e32 v3, v0
	v_mov_b32_e32 v8, v0
	v_mov_b32_e32 v9, v0
	v_mov_b32_e32 v10, v0
	v_mov_b32_e32 v11, v0
	v_mov_b32_e32 v16, v0
	v_mov_b32_e32 v17, v0
	v_mov_b32_e32 v18, v0
	v_mov_b32_e32 v19, v0
	v_mov_b32_e32 v24, v0
	v_mov_b32_e32 v25, v0
	v_mov_b32_e32 v26, v0
	v_mov_b32_e32 v27, v0
	v_mov_b32_e32 v32, v0
	v_mov_b32_e32 v33, v0
	v_mov_b32_e32 v34, v0
	v_mov_b32_e32 v35, v0
	v_mov_b32_e32 v40, v0
	v_mov_b32_e32 v41, v0
	v_mov_b32_e32 v42, v0
	v_mov_b32_e32 v43, v0
	v_mov_b32_e32 v48, v0
	v_mov_b32_e32 v49, v0
	v_mov_b32_e32 v50, v0
	v_mov_b32_e32 v51, v0
	v_mov_b32_e32 v56, v0
	v_mov_b32_e32 v57, v0
	v_mov_b32_e32 v58, v0
	v_mov_b32_e32 v59, v0
	v_mov_b32_e32 v4, v0
	v_mov_b32_e32 v5, v0
	v_mov_b32_e32 v6, v0
	v_mov_b32_e32 v7, v0
	v_mov_b32_e32 v12, v0
	v_mov_b32_e32 v13, v0
	v_mov_b32_e32 v14, v0
	v_mov_b32_e32 v15, v0
	v_mov_b32_e32 v20, v0
	v_mov_b32_e32 v21, v0
	v_mov_b32_e32 v22, v0
	v_mov_b32_e32 v23, v0
	v_mov_b32_e32 v28, v0
	v_mov_b32_e32 v29, v0
	v_mov_b32_e32 v30, v0
	v_mov_b32_e32 v31, v0
	v_mov_b32_e32 v36, v0
	v_mov_b32_e32 v37, v0
	v_mov_b32_e32 v38, v0
	v_mov_b32_e32 v39, v0
	v_mov_b32_e32 v44, v0
	v_mov_b32_e32 v45, v0
	v_mov_b32_e32 v46, v0
	v_mov_b32_e32 v47, v0
	v_mov_b32_e32 v52, v0
	v_mov_b32_e32 v53, v0
	v_mov_b32_e32 v54, v0
	v_mov_b32_e32 v55, v0
	v_mov_b32_e32 v60, v0
	v_mov_b32_e32 v61, v0
	v_mov_b32_e32 v62, v0
	v_mov_b32_e32 v63, v0
	v_mov_b32_e32 v64, v0
	v_mov_b32_e32 v65, v0
	v_mov_b32_e32 v66, v0
	v_mov_b32_e32 v67, v0
	v_mov_b32_e32 v72, v0
	v_mov_b32_e32 v73, v0
	v_mov_b32_e32 v74, v0
	v_mov_b32_e32 v75, v0
	v_mov_b32_e32 v80, v0
	v_mov_b32_e32 v81, v0
	v_mov_b32_e32 v82, v0
	v_mov_b32_e32 v83, v0
	v_mov_b32_e32 v88, v0
	v_mov_b32_e32 v89, v0
	v_mov_b32_e32 v90, v0
	v_mov_b32_e32 v91, v0
	v_mov_b32_e32 v96, v0
	v_mov_b32_e32 v97, v0
	v_mov_b32_e32 v98, v0
	v_mov_b32_e32 v99, v0
	v_mov_b32_e32 v104, v0
	v_mov_b32_e32 v105, v0
	v_mov_b32_e32 v106, v0
	v_mov_b32_e32 v107, v0
	v_mov_b32_e32 v112, v0
	v_mov_b32_e32 v113, v0
	v_mov_b32_e32 v114, v0
	v_mov_b32_e32 v115, v0
	v_mov_b32_e32 v120, v0
	v_mov_b32_e32 v121, v0
	v_mov_b32_e32 v122, v0
	v_mov_b32_e32 v123, v0
	v_mov_b32_e32 v68, v0
	v_mov_b32_e32 v69, v0
	v_mov_b32_e32 v70, v0
	v_mov_b32_e32 v71, v0
	v_mov_b32_e32 v76, v0
	v_mov_b32_e32 v77, v0
	v_mov_b32_e32 v78, v0
	v_mov_b32_e32 v79, v0
	v_mov_b32_e32 v84, v0
	v_mov_b32_e32 v85, v0
	v_mov_b32_e32 v86, v0
	v_mov_b32_e32 v87, v0
	v_mov_b32_e32 v92, v0
	v_mov_b32_e32 v93, v0
	v_mov_b32_e32 v94, v0
	v_mov_b32_e32 v95, v0
	v_mov_b32_e32 v100, v0
	v_mov_b32_e32 v101, v0
	v_mov_b32_e32 v102, v0
	v_mov_b32_e32 v103, v0
	v_mov_b32_e32 v108, v0
	v_mov_b32_e32 v109, v0
	v_mov_b32_e32 v110, v0
	v_mov_b32_e32 v111, v0
	v_mov_b32_e32 v116, v0
	v_mov_b32_e32 v117, v0
	v_mov_b32_e32 v118, v0
	v_mov_b32_e32 v119, v0
	v_mov_b32_e32 v124, v0
	v_mov_b32_e32 v125, v0
	v_mov_b32_e32 v126, v0
	v_mov_b32_e32 v127, v0
	.p2align	6
